# v24 + attn0: QK(next) MFMAs/K reads interleaved with the row-max tree of the same wave (fast path: both blocks fully active, no causal-diagonal lanes)
# baseline (speedup 1.0000x reference)
; #define MFMA32(a, b, c) __builtin_amdgcn_mfma_f32_32x32x16_bf16((a), (b), (c), 0, 0, 0)
; DI unsigned pk_bf16(float a, float b) { f32x2 v = {a, b}; bf2_t r = __builtin_convertvector(v, bf2_t); return __builtin_bit_cast(unsigned, r); }
;     ...
;         auto qk = [&](f32x16 (&s)[2], float& mi, int stg) {
;             const unsigned char* kb_ = lds + stg * STG + koff;
;             const unsigned mb = pk_bf16((m > -1e29f) ? -m : 0.f, 0.f) & 0xffffu;
;             mi = -__uint_as_float(mb << 16);
;             u32x4 qxw; qxw.x = hh ? 0u : mb; qxw.y = 0u; qxw.z = 0u; qxw.w = 0u;
;             u32x4 kxw; kxw.x = hh ? 0u : 0x3f80u; kxw.y = 0u; kxw.z = 0u; kxw.w = 0u;
;             const bf16x8 qx = __builtin_bit_cast(bf16x8, qxw), kx = __builtin_bit_cast(bf16x8, kxw);
;             f32x16 zero;
; #pragma unroll
;             for (int i = 0; i < 16; ++i) zero[i] = 0.f;
; #pragma unroll
;             for (int blk = 0; blk < 2; ++blk) {
;                 s[blk] = MFMA32(kx, qx, zero);
; #pragma unroll
;                 for (int ks = 0; ks < 4; ++ks) {
;                     const bf16x8 kf = *(const bf16x8*)(kb_ + blk * 4608 + ks * 32);
;                     s[blk] = MFMA32(kf, qf[ks], s[blk]);
;                 }
;             }
;         };
;     ...
;             if (kk + 1 < ntl && (kt + 1) * 64 <= qw0 + 31) qk(s_nxt, mi_nxt, (kk + 1) % 3);
;             if (kt * 64 <= qw0 + 31) softmax_pv(s_cur, mi_cur, kt, kk % 3);
.LBB0_1261:
	s_mul_hi_u32 s0, s45, 0xaaaaaaab
	s_lshr_b32 s60, s0, 1
	s_add_i32 s17, s16, 1
	s_cmp_lt_i32 s17, s96
	s_cselect_b64 s[0:1], -1, 0
	s_sub_i32 s8, s58, 30
	v_cmp_le_i32_e32 vcc, s8, v186
	s_mul_i32 s60, s60, 0x1a400
	s_and_b64 s[0:1], s[0:1], vcc
	s_sub_i32 s61, s58, 63
	v_cmp_le_i32_e64 s[98:99], s61, v197
	v_cmp_gt_i32_e64 s[100:101], s58, v186
	s_nop 1
	s_and_b64 s[98:99], s[98:99], s[0:1]
	s_andn2_b64 s[98:99], s[98:99], s[100:101]
	s_cmp_eq_u64 s[98:99], exec
	s_cbranch_scc1 .Lil0a_fast
	s_and_saveexec_b64 s[12:13], s[0:1]
	s_cbranch_execz .LBB0_1263
	v_cmp_lt_f32_e64 s[8:9], s90, v207
	s_mov_b64 vcc, s[2:3]
	v_subrev_u32_e32 v4, s60, v236
	v_cndmask_b32_e64 v2, 0, -v207, s[8:9]
	v_cvt_pk_bf16_f32 v7, v2, 0
	v_cndmask_b32_sdwa v2, v3, v7, vcc dst_sel:DWORD dst_unused:UNUSED_PAD src0_sel:DWORD src1_sel:WORD_0
	v_add3_u32 v16, v235, s56, v4
	v_mov_b32_e32 v4, v3
	v_mov_b32_e32 v5, v3
	ds_read_b128 v[8:11], v16 offset:35840
	ds_read_b128 v[12:15], v16 offset:35872
	v_mfma_f32_32x32x16_bf16 v[18:33], v[146:149], v[2:5], 0
	v_lshlrev_b32_e32 v2, 16, v7
	v_xor_b32_e32 v208, 0x80000000, v2
	s_waitcnt lgkmcnt(1)
	v_mfma_f32_32x32x16_bf16 v[34:49], v[8:11], v[150:153], v[18:33]
	s_waitcnt lgkmcnt(0)
	v_mfma_f32_32x32x16_bf16 v[34:49], v[12:15], v[158:161], v[34:49]
	ds_read_b128 v[8:11], v16 offset:35904
	ds_read_b128 v[12:15], v16 offset:35936
	s_waitcnt lgkmcnt(1)
	v_mfma_f32_32x32x16_bf16 v[34:49], v[8:11], v[162:165], v[34:49]
	s_waitcnt lgkmcnt(0)
	v_mfma_f32_32x32x16_bf16 v[34:49], v[12:15], v[154:157], v[34:49]
	ds_read_b128 v[8:11], v16 offset:40448
	ds_read_b128 v[12:15], v16 offset:40480
	s_waitcnt lgkmcnt(1)
	v_mfma_f32_32x32x16_bf16 v[18:33], v[8:11], v[150:153], v[18:33]
	s_waitcnt lgkmcnt(0)
	v_mfma_f32_32x32x16_bf16 v[18:33], v[12:15], v[158:161], v[18:33]
	ds_read_b128 v[8:11], v16 offset:40512
	ds_read_b128 v[12:15], v16 offset:40544
	s_waitcnt lgkmcnt(1)
	v_mfma_f32_32x32x16_bf16 v[18:33], v[8:11], v[162:165], v[18:33]
	s_waitcnt lgkmcnt(0)
	v_mfma_f32_32x32x16_bf16 v[18:33], v[12:15], v[154:157], v[18:33]

;     ...
;             if (__ballot(shift != 0.f) != 0) {
;                 if (__ballot(up) != 0) {
;                     const float alpha = __builtin_amdgcn_exp2f(m - mn);
;                     l *= alpha;
; #pragma unroll
;                     for (int db = 0; db < DVB; ++db)
; #pragma unroll
;                         for (int i = 0; i < 16; ++i) o[db][i] *= alpha;
;                     m = mn;
;                 }
.Lil0a_cont:
	v_cndmask_b32_e64 v5, 0, 1, s[8:9]
	v_cmp_ne_u32_e32 vcc, 0, v5
	s_cbranch_vccz .LBB0_1271
	v_sub_f32_e32 v5, v207, v4
	v_exp_f32_e32 v8, v5
	s_nop 0
	v_mul_f32_e32 v6, v6, v8
	v_pk_mul_f32 v[112:113], v[112:113], v[8:9] op_sel_hi:[1,0]
	v_pk_mul_f32 v[110:111], v[110:111], v[8:9] op_sel_hi:[1,0]
	v_pk_mul_f32 v[108:109], v[108:109], v[8:9] op_sel_hi:[1,0]
	v_pk_mul_f32 v[106:107], v[106:107], v[8:9] op_sel_hi:[1,0]
	v_pk_mul_f32 v[104:105], v[104:105], v[8:9] op_sel_hi:[1,0]
	v_pk_mul_f32 v[102:103], v[102:103], v[8:9] op_sel_hi:[1,0]
	v_pk_mul_f32 v[100:101], v[100:101], v[8:9] op_sel_hi:[1,0]
	v_pk_mul_f32 v[98:99], v[98:99], v[8:9] op_sel_hi:[1,0]
	v_pk_mul_f32 v[96:97], v[96:97], v[8:9] op_sel_hi:[1,0]
	v_pk_mul_f32 v[94:95], v[94:95], v[8:9] op_sel_hi:[1,0]
	v_pk_mul_f32 v[92:93], v[92:93], v[8:9] op_sel_hi:[1,0]
	v_pk_mul_f32 v[90:91], v[90:91], v[8:9] op_sel_hi:[1,0]
	v_pk_mul_f32 v[88:89], v[88:89], v[8:9] op_sel_hi:[1,0]
	v_pk_mul_f32 v[86:87], v[86:87], v[8:9] op_sel_hi:[1,0]
	v_pk_mul_f32 v[84:85], v[84:85], v[8:9] op_sel_hi:[1,0]
	v_pk_mul_f32 v[82:83], v[82:83], v[8:9] op_sel_hi:[1,0]
	v_pk_mul_f32 v[80:81], v[80:81], v[8:9] op_sel_hi:[1,0]
	v_pk_mul_f32 v[78:79], v[78:79], v[8:9] op_sel_hi:[1,0]
	v_pk_mul_f32 v[76:77], v[76:77], v[8:9] op_sel_hi:[1,0]
	v_pk_mul_f32 v[74:75], v[74:75], v[8:9] op_sel_hi:[1,0]
	v_pk_mul_f32 v[72:73], v[72:73], v[8:9] op_sel_hi:[1,0]
	v_pk_mul_f32 v[70:71], v[70:71], v[8:9] op_sel_hi:[1,0]
	v_pk_mul_f32 v[68:69], v[68:69], v[8:9] op_sel_hi:[1,0]
	v_pk_mul_f32 v[66:67], v[66:67], v[8:9] op_sel_hi:[1,0]
	v_pk_mul_f32 v[64:65], v[64:65], v[8:9] op_sel_hi:[1,0]
	v_pk_mul_f32 v[62:63], v[62:63], v[8:9] op_sel_hi:[1,0]
	v_pk_mul_f32 v[60:61], v[60:61], v[8:9] op_sel_hi:[1,0]
	v_pk_mul_f32 v[58:59], v[58:59], v[8:9] op_sel_hi:[1,0]
	v_pk_mul_f32 v[56:57], v[56:57], v[8:9] op_sel_hi:[1,0]
	v_pk_mul_f32 v[54:55], v[54:55], v[8:9] op_sel_hi:[1,0]
	v_pk_mul_f32 v[52:53], v[52:53], v[8:9] op_sel_hi:[1,0]
	v_pk_mul_f32 v[50:51], v[50:51], v[8:9] op_sel_hi:[1,0]
	s_branch .LBB0_1272

; #define MFMA32(a, b, c) __builtin_amdgcn_mfma_f32_32x32x16_bf16((a), (b), (c), 0, 0, 0)
; DI unsigned pk_bf16(float a, float b) { f32x2 v = {a, b}; bf2_t r = __builtin_convertvector(v, bf2_t); return __builtin_bit_cast(unsigned, r); }
;     ...
;         auto qk = [&](f32x16 (&s)[2], float& mi, int stg) {
;             const unsigned char* kb_ = lds + stg * STG + koff;
;             const unsigned mb = pk_bf16((m > -1e29f) ? -m : 0.f, 0.f) & 0xffffu;
;             mi = -__uint_as_float(mb << 16);
;             u32x4 qxw; qxw.x = hh ? 0u : mb; qxw.y = 0u; qxw.z = 0u; qxw.w = 0u;
;             u32x4 kxw; kxw.x = hh ? 0u : 0x3f80u; kxw.y = 0u; kxw.z = 0u; kxw.w = 0u;
;             const bf16x8 qx = __builtin_bit_cast(bf16x8, qxw), kx = __builtin_bit_cast(bf16x8, kxw);
;             f32x16 zero;
; #pragma unroll
;             for (int i = 0; i < 16; ++i) zero[i] = 0.f;
; #pragma unroll
;             for (int blk = 0; blk < 2; ++blk) {
;                 s[blk] = MFMA32(kx, qx, zero);
; #pragma unroll
;                 for (int ks = 0; ks < 4; ++ks) {
;                     const bf16x8 kf = *(const bf16x8*)(kb_ + blk * 4608 + ks * 32);
;                     s[blk] = MFMA32(kf, qf[ks], s[blk]);
;                 }
;             }
;         };
;     ...
;             if (kk + 1 < ntl && (kt + 1) * 64 <= qw0 + 31) qk(s_nxt, mi_nxt, (kk + 1) % 3);
;             if (kt * 64 <= qw0 + 31) softmax_pv(s_cur, mi_cur, kt, kk % 3);
.LBB0_1279:
	s_cmp_lt_i32 s97, s96
	s_cselect_b64 s[8:9], -1, 0
	s_add_i32 s1, s58, 34
	v_cmp_le_i32_e32 vcc, s1, v186
	s_and_b64 s[10:11], s[8:9], vcc
	s_add_i32 s61, s58, 1
	v_cmp_le_i32_e64 s[98:99], s61, v197
	s_add_i32 s61, s58, 64
	v_cmp_gt_i32_e64 s[100:101], s61, v186
	s_nop 1
	s_and_b64 s[98:99], s[98:99], s[10:11]
	s_andn2_b64 s[98:99], s[98:99], s[100:101]
	s_cmp_eq_u64 s[98:99], exec
	s_cbranch_scc1 .Lil0b_fast
	s_and_saveexec_b64 s[8:9], s[10:11]
	s_cbranch_execz .LBB0_1281
	v_cmp_lt_f32_e32 vcc, s90, v207
	v_subrev_u32_e32 v4, s0, v244
	v_add_u32_e32 v16, s56, v235
	v_cndmask_b32_e64 v2, 0, -v207, vcc
	v_cvt_pk_bf16_f32 v7, v2, 0
	v_and_b32_e32 v2, 0xffff, v7
	v_add_u32_e32 v8, v16, v4
	v_cndmask_b32_e64 v2, 0, v2, s[2:3]
	v_mov_b32_e32 v4, v3
	v_mov_b32_e32 v5, v3
	ds_read_b128 v[8:11], v8
	s_nop 0
	v_mfma_f32_32x32x16_bf16 v[114:129], v[146:149], v[2:5], 0
	v_subrev_u32_e32 v2, s0, v243
	v_add_u32_e32 v2, v16, v2
	ds_read_b128 v[12:15], v2
	v_subrev_u32_e32 v2, s0, v242
	v_add_u32_e32 v2, v16, v2
	s_waitcnt lgkmcnt(1)
	v_mfma_f32_32x32x16_bf16 v[130:145], v[8:11], v[150:153], v[114:129]
	ds_read_b128 v[8:11], v2
	v_subrev_u32_e32 v2, s0, v241
	v_add_u32_e32 v2, v16, v2
	s_waitcnt lgkmcnt(1)
	v_mfma_f32_32x32x16_bf16 v[130:145], v[12:15], v[158:161], v[130:145]
	ds_read_b128 v[12:15], v2
	v_subrev_u32_e32 v2, s0, v240
	v_add_u32_e32 v2, v16, v2
	s_waitcnt lgkmcnt(1)
	v_mfma_f32_32x32x16_bf16 v[130:145], v[8:11], v[162:165], v[130:145]
	s_waitcnt lgkmcnt(0)
	v_mfma_f32_32x32x16_bf16 v[130:145], v[12:15], v[154:157], v[130:145]
	ds_read_b128 v[8:11], v2
	ds_read_b128 v[12:15], v2 offset:32
	s_waitcnt lgkmcnt(1)
	v_mfma_f32_32x32x16_bf16 v[114:129], v[8:11], v[150:153], v[114:129]
	s_waitcnt lgkmcnt(0)
	v_mfma_f32_32x32x16_bf16 v[114:129], v[12:15], v[158:161], v[114:129]
	ds_read_b128 v[8:11], v2 offset:64
	ds_read_b128 v[12:15], v2 offset:96
	v_lshlrev_b32_e32 v2, 16, v7
	v_xor_b32_e32 v206, 0x80000000, v2
	s_waitcnt lgkmcnt(1)
	v_mfma_f32_32x32x16_bf16 v[114:129], v[8:11], v[162:165], v[114:129]
	s_waitcnt lgkmcnt(0)
	v_mfma_f32_32x32x16_bf16 v[114:129], v[12:15], v[154:157], v[114:129]

; #define MFMA32(a, b, c) __builtin_amdgcn_mfma_f32_32x32x16_bf16((a), (b), (c), 0, 0, 0)
;     ...
;             const unsigned mb = pk_bf16((m > -1e29f) ? -m : 0.f, 0.f) & 0xffffu;
;             mi = -__uint_as_float(mb << 16);
;             u32x4 qxw; qxw.x = hh ? 0u : mb; qxw.y = 0u; qxw.z = 0u; qxw.w = 0u;
;             u32x4 kxw; kxw.x = hh ? 0u : 0x3f80u; kxw.y = 0u; kxw.z = 0u; kxw.w = 0u;
;             const bf16x8 qx = __builtin_bit_cast(bf16x8, qxw), kx = __builtin_bit_cast(bf16x8, kxw);
;             f32x16 zero;
; #pragma unroll
;             for (int i = 0; i < 16; ++i) zero[i] = 0.f;
; #pragma unroll
;             for (int blk = 0; blk < 2; ++blk) {
;                 s[blk] = MFMA32(kx, qx, zero);
; #pragma unroll
;                 for (int ks = 0; ks < 4; ++ks) {
;                     const bf16x8 kf = *(const bf16x8*)(kb_ + blk * 4608 + ks * 32);
;                     s[blk] = MFMA32(kf, qf[ks], s[blk]);
;                 }
;             }
;         };
;         auto softmax_pv = [&](f32x16 (&s)[2], const float mi, int kt, int stg) {
;             const int k0 = kt * 64;
;             const unsigned char* sb = lds + stg * STG;
;             if (DRY != 1) {
;             if (MODE == 1) {
; #pragma unroll
;                 for (int blk = 0; blk < 2; ++blk)
; #pragma unroll
;                     for (int g = 0; g < 4; ++g) {
;                         const f32x4 c4 = *(const f32x4*)(sb + CK_OFF + (32 * blk + 8 * g + 4 * hh) * 4);
; #pragma unroll
;                         for (int e = 0; e < 4; ++e) s[blk][4 * g + e] -= c4[e];
;                     }
;             }
;             if (MODE == 2) {
;                 const u64 wsh = wcur >> (4 * hh);
;                 const int wlo = (int)(unsigned)wsh, whi = (int)(unsigned)(wsh >> 32);
; #pragma unroll
;                 for (int i = 0; i < 16; ++i) {
;                     const int bit = (i & 3) + 8 * (i >> 2);
;                     const unsigned m0 = (unsigned)__builtin_amdgcn_sbfe(wlo, bit, 1), m1 = (unsigned)__builtin_amdgcn_sbfe(whi, bit, 1);
;                     s[0][i] = __uint_as_float((__float_as_uint(s[0][i]) & m0) | (0xff800000u & ~m0));
;                     s[1][i] = __uint_as_float((__float_as_uint(s[1][i]) & m1) | (0xff800000u & ~m1));
;                 }
;             } else if (k0 + 63 > qw0) {
; #pragma unroll
;                 for (int blk = 0; blk < 2; ++blk)
; #pragma unroll
.Lil0a_fast:
	s_mov_b64 s[12:13], exec
	v_cmp_lt_f32_e64 s[8:9], s90, v207
	s_mov_b64 vcc, s[2:3]
	v_subrev_u32_e32 v4, s60, v236
	v_cndmask_b32_e64 v2, 0, -v207, s[8:9]
	v_cvt_pk_bf16_f32 v7, v2, 0
	v_cndmask_b32_sdwa v2, v3, v7, vcc dst_sel:DWORD dst_unused:UNUSED_PAD src0_sel:DWORD src1_sel:WORD_0
	v_add3_u32 v16, v235, s56, v4
	v_mov_b32_e32 v4, v3
	v_mov_b32_e32 v5, v3
	ds_read_b128 v[8:11], v16 offset:35840
	ds_read_b128 v[12:15], v16 offset:35872
	v_mfma_f32_32x32x16_bf16 v[18:33], v[146:149], v[2:5], 0
	v_lshlrev_b32_e32 v7, 16, v7
	v_xor_b32_e32 v208, 0x80000000, v7
	v_max_f32_e32 v2, v131, v131
	v_max_f32_e32 v4, v130, v130
	v_max_f32_e32 v2, v4, v2
	s_waitcnt lgkmcnt(1)
	v_mfma_f32_32x32x16_bf16 v[34:49], v[8:11], v[150:153], v[18:33]
	v_max3_f32 v2, v2, v132, v133
	v_max3_f32 v2, v2, v134, v135
	v_max3_f32 v2, v2, v136, v137
	s_waitcnt lgkmcnt(0)
	v_mfma_f32_32x32x16_bf16 v[34:49], v[12:15], v[158:161], v[34:49]
	v_max3_f32 v2, v2, v138, v139
	v_max3_f32 v2, v2, v140, v141
	v_max3_f32 v2, v2, v142, v143
	ds_read_b128 v[8:11], v16 offset:35904
	ds_read_b128 v[12:15], v16 offset:35936
	v_max3_f32 v2, v2, v144, v145
	v_max3_f32 v2, v2, v114, v115
	v_max3_f32 v2, v2, v116, v117
	s_waitcnt lgkmcnt(1)
	v_mfma_f32_32x32x16_bf16 v[34:49], v[8:11], v[162:165], v[34:49]
	v_max3_f32 v2, v2, v118, v119
	v_max3_f32 v2, v2, v120, v121
	v_max3_f32 v2, v2, v122, v123
	s_waitcnt lgkmcnt(0)
	v_mfma_f32_32x32x16_bf16 v[34:49], v[12:15], v[154:157], v[34:49]
	v_max3_f32 v2, v2, v124, v125
	v_max3_f32 v2, v2, v126, v127
	v_max3_f32 v2, v2, v128, v129
	ds_read_b128 v[8:11], v16 offset:40448
	ds_read_b128 v[12:15], v16 offset:40480
	v_mov_b32_e32 v4, v2
	s_nop 1
	v_permlane32_swap_b32_e32 v2, v4
	s_waitcnt lgkmcnt(1)
	v_mfma_f32_32x32x16_bf16 v[18:33], v[8:11], v[150:153], v[18:33]
	v_max_f32_e32 v4, v4, v4
	v_max_f32_e32 v2, v2, v2
	v_max_f32_e32 v198, v2, v4
	s_waitcnt lgkmcnt(0)
	v_mfma_f32_32x32x16_bf16 v[18:33], v[12:15], v[158:161], v[18:33]
	v_pk_add_f32 v[4:5], v[206:207], v[198:199]
	s_nop 0
	v_cvt_pk_bf16_f32 v2, v4, 0
	ds_read_b128 v[8:11], v16 offset:40512
	ds_read_b128 v[12:15], v16 offset:40544
	v_lshlrev_b32_e32 v2, 16, v2
	v_cmp_gt_f32_e64 s[8:9], v4, v5
	s_nop 1
	s_waitcnt lgkmcnt(1)
	v_mfma_f32_32x32x16_bf16 v[18:33], v[8:11], v[162:165], v[18:33]
	v_cndmask_b32_e64 v4, v207, v2, s[8:9]
	v_sub_f32_e32 v2, v4, v206
	s_waitcnt lgkmcnt(0)
	v_mfma_f32_32x32x16_bf16 v[18:33], v[12:15], v[154:157], v[18:33]
	v_cmp_neq_f32_e32 vcc, 0, v2
	s_cbranch_vccz .LBB0_1273
	s_branch .Lil0a_cont
.Lil0b_fast:
	s_mov_b64 s[50:51], exec
	v_cmp_lt_f32_e32 vcc, s90, v207
	v_subrev_u32_e32 v4, s0, v244
	v_add_u32_e32 v16, s56, v235
	v_cndmask_b32_e64 v2, 0, -v207, vcc
	v_cvt_pk_bf16_f32 v7, v2, 0
	v_and_b32_e32 v2, 0xffff, v7
	v_add_u32_e32 v8, v16, v4
	v_cndmask_b32_e64 v2, 0, v2, s[2:3]
	v_mov_b32_e32 v4, v3
	v_mov_b32_e32 v5, v3
	ds_read_b128 v[8:11], v8
	s_nop 0
	v_mfma_f32_32x32x16_bf16 v[114:129], v[146:149], v[2:5], 0
	v_lshlrev_b32_e32 v7, 16, v7
	v_xor_b32_e32 v206, 0x80000000, v7
	v_max_f32_e32 v2, v35, v35
	v_max_f32_e32 v4, v34, v34
	v_max_f32_e32 v2, v4, v2
	v_subrev_u32_e32 v7, s0, v243
	v_add_u32_e32 v7, v16, v7
	ds_read_b128 v[12:15], v7
	v_max3_f32 v2, v2, v36, v37
	v_max3_f32 v2, v2, v38, v39
	v_max3_f32 v2, v2, v40, v41
	v_subrev_u32_e32 v7, s0, v242
	v_add_u32_e32 v7, v16, v7
	s_waitcnt lgkmcnt(1)
	v_mfma_f32_32x32x16_bf16 v[130:145], v[8:11], v[150:153], v[114:129]
	v_max3_f32 v2, v2, v42, v43
	v_max3_f32 v2, v2, v44, v45
	v_max3_f32 v2, v2, v46, v47
	ds_read_b128 v[8:11], v7
	v_max3_f32 v2, v2, v48, v49
	v_max3_f32 v2, v2, v18, v19
	v_max3_f32 v2, v2, v20, v21
	v_subrev_u32_e32 v7, s0, v241
	v_add_u32_e32 v7, v16, v7
	s_waitcnt lgkmcnt(1)
	v_mfma_f32_32x32x16_bf16 v[130:145], v[12:15], v[158:161], v[130:145]
	v_max3_f32 v2, v2, v22, v23
	v_max3_f32 v2, v2, v24, v25
	v_max3_f32 v2, v2, v26, v27
	ds_read_b128 v[12:15], v7
	v_max3_f32 v2, v2, v28, v29
	v_max3_f32 v2, v2, v30, v31
	v_max3_f32 v2, v2, v32, v33
	v_subrev_u32_e32 v7, s0, v240
	v_add_u32_e32 v7, v16, v7
	s_waitcnt lgkmcnt(1)
	v_mfma_f32_32x32x16_bf16 v[130:145], v[8:11], v[162:165], v[130:145]
	v_mov_b32_e32 v4, v2
	s_nop 1
	v_permlane32_swap_b32_e32 v2, v4
	s_waitcnt lgkmcnt(0)
	v_mfma_f32_32x32x16_bf16 v[130:145], v[12:15], v[154:157], v[130:145]
	v_max_f32_e32 v4, v4, v4
	v_max_f32_e32 v2, v2, v2
	v_max_f32_e32 v198, v2, v4
	ds_read_b128 v[8:11], v7
	ds_read_b128 v[12:15], v7 offset:32
	v_mov_b32_e32 v209, v207
	v_pk_add_f32 v[4:5], v[208:209], v[198:199]
	s_nop 0
	s_waitcnt lgkmcnt(1)
	v_mfma_f32_32x32x16_bf16 v[114:129], v[8:11], v[150:153], v[114:129]
	v_cvt_pk_bf16_f32 v2, v4, 0
	v_lshlrev_b32_e32 v2, 16, v2
	v_cmp_gt_f32_e64 s[8:9], v4, v5
	s_waitcnt lgkmcnt(0)
	v_mfma_f32_32x32x16_bf16 v[114:129], v[12:15], v[158:161], v[114:129]
	s_nop 1
	v_cndmask_b32_e64 v4, v207, v2, s[8:9]
	v_sub_f32_e32 v2, v4, v208
	ds_read_b128 v[8:11], v7 offset:64
	ds_read_b128 v[12:15], v7 offset:96
	s_waitcnt lgkmcnt(1)
	v_mfma_f32_32x32x16_bf16 v[114:129], v[8:11], v[162:165], v[114:129]
	s_waitcnt lgkmcnt(0)
	v_mfma_f32_32x32x16_bf16 v[114:129], v[12:15], v[154:157], v[114:129]
	v_cmp_neq_f32_e32 vcc, 0, v2
	s_cbranch_vccz .LBB0_1291
	s_branch .Lil0b_cont

; __global__ void __launch_bounds__(NTHREADS) fwd_megakernel(Params p) {
;     extern __shared__ __attribute__((aligned(16))) unsigned char lds[];
	.amdhsa_kernel _Z14fwd_megakernel6Params
		.amdhsa_group_segment_fixed_size 0
		.amdhsa_private_segment_fixed_size 0
		.amdhsa_kernarg_size 456
		.amdhsa_user_sgpr_count 2
		.amdhsa_user_sgpr_dispatch_ptr 0
		.amdhsa_user_sgpr_queue_ptr 0
		.amdhsa_user_sgpr_kernarg_segment_ptr 1
		.amdhsa_user_sgpr_dispatch_id 0
		.amdhsa_user_sgpr_kernarg_preload_length 0
		.amdhsa_user_sgpr_kernarg_preload_offset 0
		.amdhsa_user_sgpr_private_segment_size 0
		.amdhsa_uses_dynamic_stack 0
		.amdhsa_enable_private_segment 0
		.amdhsa_system_sgpr_workgroup_id_x 1
		.amdhsa_system_sgpr_workgroup_id_y 0
		.amdhsa_system_sgpr_workgroup_id_z 0
		.amdhsa_system_sgpr_workgroup_info 0
		.amdhsa_system_vgpr_workitem_id 2
		.amdhsa_next_free_vgpr 256
		.amdhsa_next_free_sgpr 102
		.amdhsa_accum_offset 256
		.amdhsa_reserve_vcc 1
		.amdhsa_float_round_mode_32 0
		.amdhsa_float_round_mode_16_64 0
		.amdhsa_float_denorm_mode_32 3
		.amdhsa_float_denorm_mode_16_64 3
		.amdhsa_dx10_clamp 1
		.amdhsa_ieee_mode 1
		.amdhsa_fp16_overflow 0
		.amdhsa_tg_split 0
		.amdhsa_exception_fp_ieee_invalid_op 0
		.amdhsa_exception_fp_denorm_src 0
		.amdhsa_exception_fp_ieee_div_zero 0
		.amdhsa_exception_fp_ieee_overflow 0
		.amdhsa_exception_fp_ieee_underflow 0
		.amdhsa_exception_fp_ieee_inexact 0
		.amdhsa_exception_int_div_zero 0
	.end_amdhsa_kernel

; __global__ void __launch_bounds__(NTHREADS) fwd_megakernel(Params p) {
;     extern __shared__ __attribute__((aligned(16))) unsigned char lds[];
amdhsa.kernels:
  - .agpr_count:     0
    .args:
      - .offset:         0
        .size:           200
        .value_kind:     by_value
      - .offset:         200
        .size:           4
        .value_kind:     hidden_block_count_x
      - .offset:         204
        .size:           4
        .value_kind:     hidden_block_count_y
      - .offset:         208
        .size:           4
        .value_kind:     hidden_block_count_z
      - .offset:         212
        .size:           2
        .value_kind:     hidden_group_size_x
      - .offset:         214
        .size:           2
        .value_kind:     hidden_group_size_y
      - .offset:         216
        .size:           2
        .value_kind:     hidden_group_size_z
      - .offset:         218
        .size:           2
        .value_kind:     hidden_remainder_x
      - .offset:         220
        .size:           2
        .value_kind:     hidden_remainder_y
      - .offset:         222
        .size:           2
        .value_kind:     hidden_remainder_z
      - .offset:         240
        .size:           8
        .value_kind:     hidden_global_offset_x
      - .offset:         248
        .size:           8
        .value_kind:     hidden_global_offset_y
      - .offset:         256
        .size:           8
        .value_kind:     hidden_global_offset_z
      - .offset:         264
        .size:           2
        .value_kind:     hidden_grid_dims
      - .offset:         288
        .size:           8
        .value_kind:     hidden_multigrid_sync_arg
      - .offset:         320
        .size:           4
        .value_kind:     hidden_dynamic_lds_size
    .group_segment_fixed_size: 0
    .kernarg_segment_align: 8
    .kernarg_segment_size: 456
    .language:       OpenCL C
    .language_version:
      - 2
      - 0
    .max_flat_workgroup_size: 512
    .name:           _Z14fwd_megakernel6Params
    .private_segment_fixed_size: 0
    .sgpr_count:     108
    .sgpr_spill_count: 6
    .symbol:         _Z14fwd_megakernel6Params.kd
    .uniform_work_group_size: 1
    .uses_dynamic_stack: false
    .vgpr_count:     256
    .vgpr_spill_count: 0
    .wavefront_size: 64
